# barrier leader: write-back fully awaited, then the L1 invalidate issued right before the cross-XCD arrival atomic so it completes in that atomic's round trip (no reliance on completion order of cache
# baseline (speedup 1.0000x reference)
; __device__ __forceinline__ unsigned xb_add(unsigned* p, unsigned v) { return __hip_atomic_fetch_add(p, v, __ATOMIC_RELAXED, __HIP_MEMORY_SCOPE_AGENT); }
; __device__ __forceinline__ void xcd_barrier(const XcdBarrier& b, int xtid) {
;     ...
;         if (old + 1u == (gen + 1u) * nloc) {
;             __builtin_amdgcn_fence(__ATOMIC_RELEASE, "agent");
;             asm volatile("s_waitcnt vmcnt(0)" ::: "memory");
;             const unsigned og = xb_add(&bar[XB_TOP], 1u);
.LBB0_137:
	s_andn2_saveexec_b64 s[6:7], s[6:7]
	s_cbranch_execz .LBB0_157
	s_mov_b64 s[6:7], exec
	buffer_wbl2 sc1
	s_waitcnt lgkmcnt(0)
	s_waitcnt vmcnt(0)
	buffer_inv sc1
	v_mbcnt_lo_u32_b32 v1, s6, 0
	v_mbcnt_hi_u32_b32 v1, s7, v1
	v_cmp_eq_u32_e32 vcc, 0, v1
	s_and_saveexec_b64 s[8:9], vcc
	s_cbranch_execz .LBB0_140
	s_bcnt1_i32_b64 s6, s[6:7]
	v_mov_b32_e32 v2, s6
	v_readlane_b32 s6, v253, 14
	v_readlane_b32 s7, v253, 15
	s_nop 4
	global_atomic_add v2, v161, v2, s[6:7] sc0

; __device__ __forceinline__ unsigned xb_add(unsigned* p, unsigned v) { return __hip_atomic_fetch_add(p, v, __ATOMIC_RELAXED, __HIP_MEMORY_SCOPE_AGENT); }
; __device__ __forceinline__ void xcd_barrier(const XcdBarrier& b, int xtid) {
;     ...
;         if (old + 1u == (gen + 1u) * nloc) {
;             __builtin_amdgcn_fence(__ATOMIC_RELEASE, "agent");
;             asm volatile("s_waitcnt vmcnt(0)" ::: "memory");
;             const unsigned og = xb_add(&bar[XB_TOP], 1u);
.LBB0_255:
	s_andn2_saveexec_b64 s[8:9], s[8:9]
	s_cbranch_execz .LBB0_275
	s_mov_b64 s[8:9], exec
	buffer_wbl2 sc1
	s_waitcnt lgkmcnt(0)
	s_waitcnt vmcnt(0)
	buffer_inv sc1
	v_mbcnt_lo_u32_b32 v1, s8, 0
	v_mbcnt_hi_u32_b32 v1, s9, v1
	v_cmp_eq_u32_e32 vcc, 0, v1
	s_and_saveexec_b64 s[10:11], vcc
	s_cbranch_execz .LBB0_258
	s_bcnt1_i32_b64 s8, s[8:9]
	v_mov_b32_e32 v2, s8
	v_readlane_b32 s8, v253, 14
	v_readlane_b32 s9, v253, 15
	s_nop 4
	global_atomic_add v2, v161, v2, s[8:9] sc0

; __device__ __forceinline__ unsigned xb_add(unsigned* p, unsigned v) { return __hip_atomic_fetch_add(p, v, __ATOMIC_RELAXED, __HIP_MEMORY_SCOPE_AGENT); }
; __device__ __forceinline__ void xcd_barrier(const XcdBarrier& b, int xtid) {
;     ...
;         if (old + 1u == (gen + 1u) * nloc) {
;             __builtin_amdgcn_fence(__ATOMIC_RELEASE, "agent");
;             asm volatile("s_waitcnt vmcnt(0)" ::: "memory");
;             const unsigned og = xb_add(&bar[XB_TOP], 1u);
.LBB0_458:
	s_andn2_saveexec_b64 s[10:11], s[10:11]
	s_cbranch_execz .LBB0_478
	s_mov_b64 s[10:11], exec
	buffer_wbl2 sc1
	s_waitcnt lgkmcnt(0)
	s_waitcnt vmcnt(0)
	buffer_inv sc1
	v_mbcnt_lo_u32_b32 v1, s10, 0
	v_mbcnt_hi_u32_b32 v1, s11, v1
	v_cmp_eq_u32_e32 vcc, 0, v1
	s_and_saveexec_b64 s[12:13], vcc
	s_cbranch_execz .LBB0_461
	s_bcnt1_i32_b64 s10, s[10:11]
	v_mov_b32_e32 v2, s10
	v_readlane_b32 s10, v253, 14
	v_readlane_b32 s11, v253, 15
	s_nop 4
	global_atomic_add v2, v161, v2, s[10:11] sc0

; __device__ __forceinline__ unsigned xb_add(unsigned* p, unsigned v) { return __hip_atomic_fetch_add(p, v, __ATOMIC_RELAXED, __HIP_MEMORY_SCOPE_AGENT); }
; __device__ __forceinline__ void xcd_barrier(const XcdBarrier& b, int xtid) {
;     ...
;         if (old + 1u == (gen + 1u) * nloc) {
;             __builtin_amdgcn_fence(__ATOMIC_RELEASE, "agent");
;             asm volatile("s_waitcnt vmcnt(0)" ::: "memory");
;             const unsigned og = xb_add(&bar[XB_TOP], 1u);
.LBB0_524:
	s_andn2_saveexec_b64 s[12:13], s[12:13]
	s_cbranch_execz .LBB0_544
	s_mov_b64 s[12:13], exec
	buffer_wbl2 sc1
	s_waitcnt lgkmcnt(0)
	s_waitcnt vmcnt(0)
	buffer_inv sc1
	v_mbcnt_lo_u32_b32 v1, s12, 0
	v_mbcnt_hi_u32_b32 v1, s13, v1
	v_cmp_eq_u32_e32 vcc, 0, v1
	s_and_saveexec_b64 s[14:15], vcc
	s_cbranch_execz .LBB0_527
	s_bcnt1_i32_b64 s12, s[12:13]
	v_mov_b32_e32 v2, s12
	v_readlane_b32 s12, v253, 14
	v_readlane_b32 s13, v253, 15
	s_nop 4
	global_atomic_add v2, v161, v2, s[12:13] sc0

; __device__ __forceinline__ unsigned xb_add(unsigned* p, unsigned v) { return __hip_atomic_fetch_add(p, v, __ATOMIC_RELAXED, __HIP_MEMORY_SCOPE_AGENT); }
; __device__ __forceinline__ void xcd_barrier(const XcdBarrier& b, int xtid) {
;     ...
;         if (old + 1u == (gen + 1u) * nloc) {
;             __builtin_amdgcn_fence(__ATOMIC_RELEASE, "agent");
;             asm volatile("s_waitcnt vmcnt(0)" ::: "memory");
;             const unsigned og = xb_add(&bar[XB_TOP], 1u);
.LBB0_1092:
	s_mov_b64 s[6:7], exec
	buffer_wbl2 sc1
	s_waitcnt lgkmcnt(0)
	s_waitcnt vmcnt(0)
	buffer_inv sc1
	v_mbcnt_lo_u32_b32 v1, s6, 0
	v_mbcnt_hi_u32_b32 v1, s7, v1
	v_cmp_eq_u32_e32 vcc, 0, v1
	s_and_saveexec_b64 s[8:9], vcc
	s_cbranch_execz .LBB0_1094
	s_bcnt1_i32_b64 s6, s[6:7]
	v_mov_b32_e32 v2, s6
	v_readlane_b32 s6, v253, 14
	v_readlane_b32 s7, v253, 15
	s_nop 4
	global_atomic_add v2, v161, v2, s[6:7] sc0
